# XR K-loops: scalar pointer arithmetic of SP1 compute tail moved behind the closing s_barrier
# speedup vs baseline: 1.0063x; 1.0062x over previous
; #define PG8_STAGEX(b, gbase) do { if constexpr (XR) { if (lane < 16) __builtin_amdgcn_global_load_lds((const unsigned*)((const char*)(gbase) + voffX), (PG8_LAS unsigned*)(lds + XR_OFF + (b) * 2048 + wid * 256), 16, 0, 0); } } while (0)
; #define PG8_LDX(b) do { if constexpr (XR) { _Pragma("unroll") for (int k = 0; k < 2; ++k) Ax_[k] = *(const PG8_LAS bf16x8*)(lds + XR_OFF + (b) * 2048 + aoffx + k * 1024); } } while (0)
; #define PG8_MMAX() do { if constexpr (XR) { if (hasx) { __builtin_amdgcn_s_setprio(1); if (wr == 0) PG8_MMAX_(B0); else PG8_MMAX_(B1); __builtin_amdgcn_s_setprio(0); } } } while (0)
; #define PG8_WAIT_LOOP() do { if constexpr (XR) PG8_WAIT_V(9); else PG8_WAIT_V(8); } while (0)
; #define PG8_STAGE(bufoff, gbase, voff) do { _Pragma("unroll") for (int _i = 0; _i < 2; ++_i) \
;         __builtin_amdgcn_global_load_lds((const unsigned*)((const char*)(gbase) + (voff)[_i]), (PG8_LAS unsigned*)(lds + (bufoff) + ldsw + _i * 8192), 16, 0, 0); } while (0)
; #define PG8_LDA(dst, b, h) do { _Pragma("unroll") for (int m = 0; m < 4; ++m) _Pragma("unroll") for (int k = 0; k < 2; ++k) dst[m][k] = *(const PG8_LAS bf16x8*)(lds + PG8_SA(b, h) + aoff + m * 2048 + k * 1024); } while (0)
; #define PG8_WAIT_L(n) asm volatile("s_waitcnt lgkmcnt(" #n ")" ::: "memory")
; template <class Epi, class Sched, bool ALIGN_EPI = false, bool SP2 = false, bool DRAIN = true, bool XR = false>
; __device__ __forceinline__ void gemm_phase(PG8_LAS unsigned char* lds, const Gemm g, const Sched& S, const Epi& E) {
;     ...
;             const char* a2 = last ? nA + ka0 : cA + PG8_KOA(t + 2); const char* b2 = last ? nB + kb0 : cB + PG8_KOB(t + 2);
;             const char* x2 = XR ? (last ? nX + kx0 : cX + PG8_KOX(t + 2)) : nullptr; const char* x3 = XR ? x2 + kstep : nullptr;
;             const char* a3 = a2 + kstep; const char* b3 = b2 + kstep;
;             if (last && has_next) S.a_ready(nxt);
;             if constexpr (SP2) {
;             PG8_LDB(B0, 0, 0); PG8_LDB(B1, 0, 1); PG8_SCHED; PG8_LDA(At, 0, 0); PG8_LDX(0); PG8_STAGE(PG8_SA(1, 1), a1 + hstepA, voffA);
;             PG8_WAIT_LOOP(); PG8_WAIT_L(0); PG8_BAR; PG8_MMA(0, 0, At, B0); PG8_MMA(0, 1, At, B1); PG8_MMAX(); PG8_BAR; PG8_SCHED;
;             PG8_LDA(At, 0, 1); PG8_STAGE(PG8_SB(0, 0), b2, voffB); PG8_STAGE(PG8_SB(0, 1), b2 + hstep, voffB); PG8_STAGE(PG8_SA(0, 0), a2, voffA); PG8_STAGEX(0, x2);
.LBB0_1226:
	s_barrier
	s_add_i32 s89, s50, 2
	s_and_b32 s48, s89, s82
	s_lshr_b32 s84, s48, 2
	s_lshl_b32 s36, s48, 7
	s_lshl_b64 vcc, s[84:85], 9
	s_and_b32 s36, s36, 0x100
	s_add_u32 s49, s18, vcc_lo
	s_addc_u32 s51, s19, vcc_hi
	s_add_u32 s36, s49, s36
	s_mov_b32 s49, s85
	s_addc_u32 s51, s51, 0
	s_lshl_b64 s[48:49], s[48:49], 7
	s_add_u32 vcc_lo, s14, s48
	s_addc_u32 vcc_hi, s15, s49
	s_add_u32 s58, s16, s48
	s_addc_u32 s59, s17, s49
	s_cmp_eq_u32 s37, s50
	s_cselect_b32 s49, s43, s51
	s_cselect_b32 s48, s42, s36
	s_cselect_b32 s51, s97, s59
	s_cselect_b32 s50, s90, s58
	s_cselect_b32 vcc_hi, s45, vcc_hi
	s_cselect_b32 vcc_lo, s44, vcc_lo
	s_mov_b32 m0, s65
	v_lshl_add_u64 v[224:225], vcc, 0, v[216:217]
	v_lshl_add_u64 v[226:227], vcc, 0, v[220:221]
	s_add_u32 vcc_lo, vcc_lo, s10
	ds_read_b128 v[198:201], v251 offset:16384
	ds_read_b128 v[202:205], v251 offset:17408
	ds_read_b128 v[190:193], v251 offset:18432
	ds_read_b128 v[194:197], v251 offset:19456
	ds_read_b128 v[182:185], v251 offset:20480
	ds_read_b128 v[186:189], v251 offset:21504
	ds_read_b128 v[174:177], v251 offset:22528
	ds_read_b128 v[178:181], v251 offset:23552
	global_load_lds_dwordx4 v[224:225], off
	s_mov_b32 m0, s67
	s_addc_u32 vcc_hi, vcc_hi, s11
	global_load_lds_dwordx4 v[226:227], off
	v_lshl_add_u64 v[228:229], vcc, 0, v[216:217]
	s_mov_b32 m0, s68
	v_lshl_add_u64 v[230:231], vcc, 0, v[220:221]
	global_load_lds_dwordx4 v[228:229], off
	s_mov_b32 m0, s69
	v_lshl_add_u64 v[232:233], s[48:49], 0, v[214:215]
	global_load_lds_dwordx4 v[230:231], off
	s_mov_b32 m0, s64
	v_lshl_add_u64 v[234:235], s[48:49], 0, v[218:219]
	global_load_lds_dwordx4 v[232:233], off
	s_mov_b32 m0, s70
	v_lshl_add_u64 v[4:5], s[50:51], 0, v[222:223]
	global_load_lds_dwordx4 v[234:235], off
	s_and_saveexec_b64 s[50:51], s[2:3]
	s_cbranch_execz .LBB0_1228
	s_add_i32 s36, s57, 0
	s_add_i32 m0, s36, 0x22400
	s_nop 0
	global_load_lds_dwordx4 v[4:5], off

; #define PG8_STAGEX(b, gbase) do { if constexpr (XR) { if (lane < 16) __builtin_amdgcn_global_load_lds((const unsigned*)((const char*)(gbase) + voffX), (PG8_LAS unsigned*)(lds + XR_OFF + (b) * 2048 + wid * 256), 16, 0, 0); } } while (0)
; #define PG8_LDX(b) do { if constexpr (XR) { _Pragma("unroll") for (int k = 0; k < 2; ++k) Ax_[k] = *(const PG8_LAS bf16x8*)(lds + XR_OFF + (b) * 2048 + aoffx + k * 1024); } } while (0)
; #define PG8_MMAX() do { if constexpr (XR) { if (hasx) { __builtin_amdgcn_s_setprio(1); if (wr == 0) PG8_MMAX_(B0); else PG8_MMAX_(B1); __builtin_amdgcn_s_setprio(0); } } } while (0)
; #define PG8_WAIT_LOOP() do { if constexpr (XR) PG8_WAIT_V(9); else PG8_WAIT_V(8); } while (0)
; #define PG8_STAGE(bufoff, gbase, voff) do { _Pragma("unroll") for (int _i = 0; _i < 2; ++_i) \
;         __builtin_amdgcn_global_load_lds((const unsigned*)((const char*)(gbase) + (voff)[_i]), (PG8_LAS unsigned*)(lds + (bufoff) + ldsw + _i * 8192), 16, 0, 0); } while (0)
; #define PG8_LDA(dst, b, h) do { _Pragma("unroll") for (int m = 0; m < 4; ++m) _Pragma("unroll") for (int k = 0; k < 2; ++k) dst[m][k] = *(const PG8_LAS bf16x8*)(lds + PG8_SA(b, h) + aoff + m * 2048 + k * 1024); } while (0)
; #define PG8_WAIT_L(n) asm volatile("s_waitcnt lgkmcnt(" #n ")" ::: "memory")
; template <class Epi, class Sched, bool ALIGN_EPI = false, bool SP2 = false, bool DRAIN = true, bool XR = false>
; __device__ __forceinline__ void gemm_phase(PG8_LAS unsigned char* lds, const Gemm g, const Sched& S, const Epi& E) {
;     ...
;             const char* a2 = last ? nA + ka0 : cA + PG8_KOA(t + 2); const char* b2 = last ? nB + kb0 : cB + PG8_KOB(t + 2);
;             const char* x2 = XR ? (last ? nX + kx0 : cX + PG8_KOX(t + 2)) : nullptr; const char* x3 = XR ? x2 + kstep : nullptr;
;             const char* a3 = a2 + kstep; const char* b3 = b2 + kstep;
;             if (last && has_next) S.a_ready(nxt);
;             if constexpr (SP2) {
;             PG8_LDB(B0, 0, 0); PG8_LDB(B1, 0, 1); PG8_SCHED; PG8_LDA(At, 0, 0); PG8_LDX(0); PG8_STAGE(PG8_SA(1, 1), a1 + hstepA, voffA);
;             PG8_WAIT_LOOP(); PG8_WAIT_L(0); PG8_BAR; PG8_MMA(0, 0, At, B0); PG8_MMA(0, 1, At, B1); PG8_MMAX(); PG8_BAR; PG8_SCHED;
;             PG8_LDA(At, 0, 1); PG8_STAGE(PG8_SB(0, 0), b2, voffB); PG8_STAGE(PG8_SB(0, 1), b2 + hstep, voffB); PG8_STAGE(PG8_SA(0, 0), a2, voffA); PG8_STAGEX(0, x2);
.LBB0_1365:
	s_barrier
	s_and_b32 s8, s90, s73
	s_lshr_b32 s84, s8, 2
	s_lshl_b32 s9, s8, 7
	s_lshl_b64 s[20:21], s[84:85], 9
	s_and_b32 s9, s9, 0x100
	s_add_u32 s20, s56, s20
	s_addc_u32 s21, s57, s21
	s_add_u32 s20, s20, s9
	s_mov_b32 s9, s85
	s_addc_u32 s21, s21, 0
	s_lshl_b64 s[8:9], s[8:9], 7
	s_add_u32 s36, s54, s8
	s_addc_u32 s62, s55, s9
	s_add_u32 s8, s58, s8
	s_addc_u32 s9, s59, s9
	s_cmp_eq_u32 s65, s90
	s_cselect_b32 s61, s49, s21
	s_cselect_b32 s60, s48, s20
	s_cselect_b32 s9, s88, s9
	s_cselect_b32 s8, s89, s8
	s_cselect_b32 s21, s51, s62
	s_cselect_b32 s20, s50, s36
	s_mov_b32 m0, s14
	v_lshl_add_u64 v[224:225], s[20:21], 0, v[218:219]
	v_lshl_add_u64 v[226:227], s[20:21], 0, v[214:215]
	s_add_u32 s20, s20, s28
	ds_read_b128 v[198:201], v249 offset:16384
	ds_read_b128 v[202:205], v249 offset:17408
	ds_read_b128 v[190:193], v249 offset:18432
	ds_read_b128 v[194:197], v249 offset:19456
	ds_read_b128 v[182:185], v249 offset:20480
	ds_read_b128 v[186:189], v249 offset:21504
	ds_read_b128 v[174:177], v249 offset:22528
	ds_read_b128 v[178:181], v249 offset:23552
	global_load_lds_dwordx4 v[224:225], off
	s_mov_b32 m0, s15
	s_addc_u32 s21, s21, s29
	global_load_lds_dwordx4 v[226:227], off
	v_lshl_add_u64 v[228:229], s[20:21], 0, v[218:219]
	s_mov_b32 m0, s16
	v_lshl_add_u64 v[230:231], s[20:21], 0, v[214:215]
	global_load_lds_dwordx4 v[228:229], off
	s_mov_b32 m0, s17
	v_lshl_add_u64 v[232:233], s[60:61], 0, v[220:221]
	global_load_lds_dwordx4 v[230:231], off
	s_mov_b32 m0, s13
	v_lshl_add_u64 v[234:235], s[60:61], 0, v[216:217]
	global_load_lds_dwordx4 v[232:233], off
	s_mov_b32 m0, s18
	v_lshl_add_u64 v[4:5], s[8:9], 0, v[222:223]
	global_load_lds_dwordx4 v[234:235], off
	s_and_saveexec_b64 s[62:63], s[0:1]
	s_cbranch_execz .LBB0_1367
	s_add_i32 s8, s12, 0
	s_add_i32 m0, s8, 0x22400
	s_nop 0
	global_load_lds_dwordx4 v[4:5], off

; #define PG8_STAGEX(b, gbase) do { if constexpr (XR) { if (lane < 16) __builtin_amdgcn_global_load_lds((const unsigned*)((const char*)(gbase) + voffX), (PG8_LAS unsigned*)(lds + XR_OFF + (b) * 2048 + wid * 256), 16, 0, 0); } } while (0)
; #define PG8_LDX(b) do { if constexpr (XR) { _Pragma("unroll") for (int k = 0; k < 2; ++k) Ax_[k] = *(const PG8_LAS bf16x8*)(lds + XR_OFF + (b) * 2048 + aoffx + k * 1024); } } while (0)
; #define PG8_MMAX() do { if constexpr (XR) { if (hasx) { __builtin_amdgcn_s_setprio(1); if (wr == 0) PG8_MMAX_(B0); else PG8_MMAX_(B1); __builtin_amdgcn_s_setprio(0); } } } while (0)
; #define PG8_WAIT_LOOP() do { if constexpr (XR) PG8_WAIT_V(9); else PG8_WAIT_V(8); } while (0)
; #define PG8_STAGE(bufoff, gbase, voff) do { _Pragma("unroll") for (int _i = 0; _i < 2; ++_i) \
;         __builtin_amdgcn_global_load_lds((const unsigned*)((const char*)(gbase) + (voff)[_i]), (PG8_LAS unsigned*)(lds + (bufoff) + ldsw + _i * 8192), 16, 0, 0); } while (0)
; #define PG8_LDA(dst, b, h) do { _Pragma("unroll") for (int m = 0; m < 4; ++m) _Pragma("unroll") for (int k = 0; k < 2; ++k) dst[m][k] = *(const PG8_LAS bf16x8*)(lds + PG8_SA(b, h) + aoff + m * 2048 + k * 1024); } while (0)
; #define PG8_WAIT_L(n) asm volatile("s_waitcnt lgkmcnt(" #n ")" ::: "memory")
; template <class Epi, class Sched, bool ALIGN_EPI = false, bool SP2 = false, bool DRAIN = true, bool XR = false>
; __device__ __forceinline__ void gemm_phase(PG8_LAS unsigned char* lds, const Gemm g, const Sched& S, const Epi& E) {
;     ...
;             const char* a2 = last ? nA + ka0 : cA + PG8_KOA(t + 2); const char* b2 = last ? nB + kb0 : cB + PG8_KOB(t + 2);
;             const char* x2 = XR ? (last ? nX + kx0 : cX + PG8_KOX(t + 2)) : nullptr; const char* x3 = XR ? x2 + kstep : nullptr;
;             const char* a3 = a2 + kstep; const char* b3 = b2 + kstep;
;             if (last && has_next) S.a_ready(nxt);
;             if constexpr (SP2) {
;             PG8_LDB(B0, 0, 0); PG8_LDB(B1, 0, 1); PG8_SCHED; PG8_LDA(At, 0, 0); PG8_LDX(0); PG8_STAGE(PG8_SA(1, 1), a1 + hstepA, voffA);
;             PG8_WAIT_LOOP(); PG8_WAIT_L(0); PG8_BAR; PG8_MMA(0, 0, At, B0); PG8_MMA(0, 1, At, B1); PG8_MMAX(); PG8_BAR; PG8_SCHED;
;             PG8_LDA(At, 0, 1); PG8_STAGE(PG8_SB(0, 0), b2, voffB); PG8_STAGE(PG8_SB(0, 1), b2 + hstep, voffB); PG8_STAGE(PG8_SA(0, 0), a2, voffA); PG8_STAGEX(0, x2);
.LBB0_1507:
	s_barrier
	s_add_i32 s64, s64, 2
	s_and_b32 s62, s64, s97
	s_lshr_b32 s84, s62, 2
	s_lshl_b32 s36, s62, 7
	s_lshl_b64 s[64:65], s[84:85], 9
	s_and_b32 s36, s36, 0x100
	s_add_u32 s63, s40, s64
	s_addc_u32 s64, s41, s65
	s_add_u32 s36, s63, s36
	s_mov_b32 s63, s85
	s_addc_u32 s64, s64, 0
	s_lshl_b64 s[62:63], s[62:63], 7
	s_add_u32 vcc_lo, s34, s62
	s_addc_u32 vcc_hi, s35, s63
	s_add_u32 s81, s42, s62
	s_addc_u32 s65, s43, s63
	s_cmp_eq_u32 s91, s70
	s_cselect_b32 s63, s8, s64
	s_cselect_b32 s62, s78, s36
	s_cselect_b32 s65, s69, s65
	s_cselect_b32 s64, s21, s81
	s_cselect_b32 vcc_hi, s20, vcc_hi
	s_cselect_b32 vcc_lo, s9, vcc_lo
	s_mov_b32 m0, s16
	v_lshl_add_u64 v[224:225], vcc, 0, v[214:215]
	v_lshl_add_u64 v[226:227], vcc, 0, v[218:219]
	s_add_u32 vcc_lo, vcc_lo, s28
	ds_read_b128 v[196:199], v249 offset:16384
	ds_read_b128 v[200:203], v249 offset:17408
	ds_read_b128 v[188:191], v249 offset:18432
	ds_read_b128 v[192:195], v249 offset:19456
	ds_read_b128 v[180:183], v249 offset:20480
	ds_read_b128 v[184:187], v249 offset:21504
	ds_read_b128 v[172:175], v249 offset:22528
	ds_read_b128 v[176:179], v249 offset:23552
	global_load_lds_dwordx4 v[224:225], off
	s_mov_b32 m0, s17
	s_addc_u32 vcc_hi, vcc_hi, s29
	global_load_lds_dwordx4 v[226:227], off
	v_lshl_add_u64 v[228:229], vcc, 0, v[214:215]
	s_mov_b32 m0, s93
	v_lshl_add_u64 v[230:231], vcc, 0, v[218:219]
	global_load_lds_dwordx4 v[228:229], off
	s_mov_b32 m0, s24
	v_lshl_add_u64 v[232:233], s[62:63], 0, v[204:205]
	global_load_lds_dwordx4 v[230:231], off
	s_mov_b32 m0, s90
	v_lshl_add_u64 v[234:235], s[62:63], 0, v[216:217]
	global_load_lds_dwordx4 v[232:233], off
	s_mov_b32 m0, s25
	v_lshl_add_u64 v[222:223], s[64:65], 0, v[220:221]
	global_load_lds_dwordx4 v[234:235], off
	s_and_saveexec_b64 s[64:65], s[2:3]
	s_cbranch_execz .LBB0_1509
	s_add_i32 s36, s26, 0
	s_add_i32 m0, s36, 0x22400
	s_nop 0
	global_load_lds_dwordx4 v[222:223], off

; #define PG8_STAGEX(b, gbase) do { if constexpr (XR) { if (lane < 16) __builtin_amdgcn_global_load_lds((const unsigned*)((const char*)(gbase) + voffX), (PG8_LAS unsigned*)(lds + XR_OFF + (b) * 2048 + wid * 256), 16, 0, 0); } } while (0)
; #define PG8_LDX(b) do { if constexpr (XR) { _Pragma("unroll") for (int k = 0; k < 2; ++k) Ax_[k] = *(const PG8_LAS bf16x8*)(lds + XR_OFF + (b) * 2048 + aoffx + k * 1024); } } while (0)
; #define PG8_MMAX() do { if constexpr (XR) { if (hasx) { __builtin_amdgcn_s_setprio(1); if (wr == 0) PG8_MMAX_(B0); else PG8_MMAX_(B1); __builtin_amdgcn_s_setprio(0); } } } while (0)
; #define PG8_WAIT_LOOP() do { if constexpr (XR) PG8_WAIT_V(9); else PG8_WAIT_V(8); } while (0)
; #define PG8_STAGE(bufoff, gbase, voff) do { _Pragma("unroll") for (int _i = 0; _i < 2; ++_i) \
;         __builtin_amdgcn_global_load_lds((const unsigned*)((const char*)(gbase) + (voff)[_i]), (PG8_LAS unsigned*)(lds + (bufoff) + ldsw + _i * 8192), 16, 0, 0); } while (0)
; #define PG8_LDA(dst, b, h) do { _Pragma("unroll") for (int m = 0; m < 4; ++m) _Pragma("unroll") for (int k = 0; k < 2; ++k) dst[m][k] = *(const PG8_LAS bf16x8*)(lds + PG8_SA(b, h) + aoff + m * 2048 + k * 1024); } while (0)
; #define PG8_WAIT_L(n) asm volatile("s_waitcnt lgkmcnt(" #n ")" ::: "memory")
; template <class Epi, class Sched, bool ALIGN_EPI = false, bool SP2 = false, bool DRAIN = true, bool XR = false>
; __device__ __forceinline__ void gemm_phase(PG8_LAS unsigned char* lds, const Gemm g, const Sched& S, const Epi& E) {
;     ...
;             const char* a2 = last ? nA + ka0 : cA + PG8_KOA(t + 2); const char* b2 = last ? nB + kb0 : cB + PG8_KOB(t + 2);
;             const char* x2 = XR ? (last ? nX + kx0 : cX + PG8_KOX(t + 2)) : nullptr; const char* x3 = XR ? x2 + kstep : nullptr;
;             const char* a3 = a2 + kstep; const char* b3 = b2 + kstep;
;             if (last && has_next) S.a_ready(nxt);
;             if constexpr (SP2) {
;             PG8_LDB(B0, 0, 0); PG8_LDB(B1, 0, 1); PG8_SCHED; PG8_LDA(At, 0, 0); PG8_LDX(0); PG8_STAGE(PG8_SA(1, 1), a1 + hstepA, voffA);
;             PG8_WAIT_LOOP(); PG8_WAIT_L(0); PG8_BAR; PG8_MMA(0, 0, At, B0); PG8_MMA(0, 1, At, B1); PG8_MMAX(); PG8_BAR; PG8_SCHED;
;             PG8_LDA(At, 0, 1); PG8_STAGE(PG8_SB(0, 0), b2, voffB); PG8_STAGE(PG8_SB(0, 1), b2 + hstep, voffB); PG8_STAGE(PG8_SA(0, 0), a2, voffA); PG8_STAGEX(0, x2);
.LBB0_1658:
	s_barrier
	s_add_i32 s46, s46, 2
	s_and_b32 s44, s46, s59
	s_lshr_b32 s84, s44, 2
	s_lshl_b32 s36, s44, 7
	s_lshl_b64 s[46:47], s[84:85], 17
	s_and_b32 s36, s36, 0x100
	s_add_u32 s45, s40, s46
	s_addc_u32 s46, s41, s47
	s_add_u32 s36, s45, s36
	s_mov_b32 s45, s85
	s_addc_u32 s46, s46, 0
	s_lshl_b64 s[44:45], s[44:45], 7
	s_add_u32 vcc_lo, s34, s44
	s_addc_u32 vcc_hi, s35, s45
	s_add_u32 s12, s42, s44
	s_addc_u32 s13, s43, s45
	s_cmp_eq_u32 s82, s89
	s_cselect_b32 s45, s39, s46
	s_cselect_b32 s44, s93, s36
	s_cselect_b32 s47, s90, s13
	s_cselect_b32 s46, s97, s12
	s_cselect_b32 vcc_hi, s96, vcc_hi
	s_cselect_b32 vcc_lo, s50, vcc_lo
	s_mov_b32 m0, s64
	v_lshl_add_u64 v[224:225], vcc, 0, v[216:217]
	v_lshl_add_u64 v[226:227], vcc, 0, v[220:221]
	s_add_u32 vcc_lo, vcc_lo, s8
	ds_read_b128 v[198:201], v249 offset:16384
	ds_read_b128 v[202:205], v249 offset:17408
	ds_read_b128 v[190:193], v249 offset:18432
	ds_read_b128 v[194:197], v249 offset:19456
	ds_read_b128 v[182:185], v249 offset:20480
	ds_read_b128 v[186:189], v249 offset:21504
	ds_read_b128 v[174:177], v249 offset:22528
	ds_read_b128 v[178:181], v249 offset:23552
	global_load_lds_dwordx4 v[224:225], off
	s_mov_b32 m0, s65
	s_addc_u32 vcc_hi, vcc_hi, s9
	global_load_lds_dwordx4 v[226:227], off
	v_lshl_add_u64 v[228:229], vcc, 0, v[216:217]
	s_mov_b32 m0, s67
	v_lshl_add_u64 v[230:231], vcc, 0, v[220:221]
	global_load_lds_dwordx4 v[228:229], off
	s_mov_b32 m0, s68
	v_lshl_add_u64 v[232:233], s[44:45], 0, v[214:215]
	global_load_lds_dwordx4 v[230:231], off
	s_mov_b32 m0, s63
	v_lshl_add_u64 v[234:235], s[44:45], 0, v[218:219]
	global_load_lds_dwordx4 v[232:233], off
	s_mov_b32 m0, s69
	v_lshl_add_u64 v[4:5], s[46:47], 0, v[222:223]
	global_load_lds_dwordx4 v[234:235], off
	s_and_saveexec_b64 s[46:47], s[2:3]
	s_cbranch_execz .LBB0_1660
	s_add_i32 s12, s60, 0
	s_add_i32 m0, s12, 0x22400
	s_nop 0
	global_load_lds_dwordx4 v[4:5], off

; #define PG8_STAGEX(b, gbase) do { if constexpr (XR) { if (lane < 16) __builtin_amdgcn_global_load_lds((const unsigned*)((const char*)(gbase) + voffX), (PG8_LAS unsigned*)(lds + XR_OFF + (b) * 2048 + wid * 256), 16, 0, 0); } } while (0)
; #define PG8_LDX(b) do { if constexpr (XR) { _Pragma("unroll") for (int k = 0; k < 2; ++k) Ax_[k] = *(const PG8_LAS bf16x8*)(lds + XR_OFF + (b) * 2048 + aoffx + k * 1024); } } while (0)
; #define PG8_MMAX() do { if constexpr (XR) { if (hasx) { __builtin_amdgcn_s_setprio(1); if (wr == 0) PG8_MMAX_(B0); else PG8_MMAX_(B1); __builtin_amdgcn_s_setprio(0); } } } while (0)
; #define PG8_WAIT_LOOP() do { if constexpr (XR) PG8_WAIT_V(9); else PG8_WAIT_V(8); } while (0)
; #define PG8_STAGE(bufoff, gbase, voff) do { _Pragma("unroll") for (int _i = 0; _i < 2; ++_i) \
;         __builtin_amdgcn_global_load_lds((const unsigned*)((const char*)(gbase) + (voff)[_i]), (PG8_LAS unsigned*)(lds + (bufoff) + ldsw + _i * 8192), 16, 0, 0); } while (0)
; #define PG8_LDA(dst, b, h) do { _Pragma("unroll") for (int m = 0; m < 4; ++m) _Pragma("unroll") for (int k = 0; k < 2; ++k) dst[m][k] = *(const PG8_LAS bf16x8*)(lds + PG8_SA(b, h) + aoff + m * 2048 + k * 1024); } while (0)
; #define PG8_WAIT_L(n) asm volatile("s_waitcnt lgkmcnt(" #n ")" ::: "memory")
; template <class Epi, class Sched, bool ALIGN_EPI = false, bool SP2 = false, bool DRAIN = true, bool XR = false>
; __device__ __forceinline__ void gemm_phase(PG8_LAS unsigned char* lds, const Gemm g, const Sched& S, const Epi& E) {
;     ...
;             const char* a2 = last ? nA + ka0 : cA + PG8_KOA(t + 2); const char* b2 = last ? nB + kb0 : cB + PG8_KOB(t + 2);
;             const char* x2 = XR ? (last ? nX + kx0 : cX + PG8_KOX(t + 2)) : nullptr; const char* x3 = XR ? x2 + kstep : nullptr;
;             const char* a3 = a2 + kstep; const char* b3 = b2 + kstep;
;             if (last && has_next) S.a_ready(nxt);
;             if constexpr (SP2) {
;             PG8_LDB(B0, 0, 0); PG8_LDB(B1, 0, 1); PG8_SCHED; PG8_LDA(At, 0, 0); PG8_LDX(0); PG8_STAGE(PG8_SA(1, 1), a1 + hstepA, voffA);
;             PG8_WAIT_LOOP(); PG8_WAIT_L(0); PG8_BAR; PG8_MMA(0, 0, At, B0); PG8_MMA(0, 1, At, B1); PG8_MMAX(); PG8_BAR; PG8_SCHED;
;             PG8_LDA(At, 0, 1); PG8_STAGE(PG8_SB(0, 0), b2, voffB); PG8_STAGE(PG8_SB(0, 1), b2 + hstep, voffB); PG8_STAGE(PG8_SA(0, 0), a2, voffA); PG8_STAGEX(0, x2);
.LBB0_1862:
	s_barrier
	s_add_i32 s56, s56, 2
	s_and_b32 s54, s56, s67
	s_lshr_b32 s84, s54, 2
	s_lshl_b32 s36, s54, 7
	s_lshl_b64 s[56:57], s[84:85], 9
	s_and_b32 s36, s36, 0x100
	s_add_u32 s55, s24, s56
	s_addc_u32 s56, s25, s57
	s_add_u32 s36, s55, s36
	s_mov_b32 s55, s85
	s_addc_u32 s56, s56, 0
	s_lshl_b64 s[54:55], s[54:55], 7
	s_add_u32 vcc_lo, s22, s54
	s_addc_u32 vcc_hi, s23, s55
	s_add_u32 s70, s28, s54
	s_addc_u32 s57, s29, s55
	s_cmp_eq_u32 s63, s45
	s_cselect_b32 s55, s59, s56
	s_cselect_b32 s54, s58, s36
	s_cselect_b32 s57, s44, s57
	s_cselect_b32 s56, s43, s70
	s_cselect_b32 vcc_hi, s42, vcc_hi
	s_cselect_b32 vcc_lo, s78, vcc_lo
	s_mov_b32 m0, s73
	v_lshl_add_u64 v[224:225], vcc, 0, v[216:217]
	v_lshl_add_u64 v[226:227], vcc, 0, v[220:221]
	s_add_u32 vcc_lo, vcc_lo, s18
	ds_read_b128 v[198:201], v238 offset:16384
	ds_read_b128 v[202:205], v238 offset:17408
	ds_read_b128 v[190:193], v238 offset:18432
	ds_read_b128 v[194:197], v238 offset:19456
	ds_read_b128 v[182:185], v238 offset:20480
	ds_read_b128 v[186:189], v238 offset:21504
	ds_read_b128 v[174:177], v238 offset:22528
	ds_read_b128 v[178:181], v238 offset:23552
	global_load_lds_dwordx4 v[224:225], off
	s_mov_b32 m0, s74
	s_addc_u32 vcc_hi, vcc_hi, s19
	global_load_lds_dwordx4 v[226:227], off
	v_lshl_add_u64 v[228:229], vcc, 0, v[216:217]
	s_mov_b32 m0, s75
	v_lshl_add_u64 v[230:231], vcc, 0, v[220:221]
	global_load_lds_dwordx4 v[228:229], off
	s_mov_b32 m0, s76
	v_lshl_add_u64 v[232:233], s[54:55], 0, v[214:215]
	global_load_lds_dwordx4 v[230:231], off
	s_mov_b32 m0, s72
	v_lshl_add_u64 v[234:235], s[54:55], 0, v[218:219]
	global_load_lds_dwordx4 v[232:233], off
	s_mov_b32 m0, s77
	v_lshl_add_u64 v[4:5], s[56:57], 0, v[222:223]
	global_load_lds_dwordx4 v[234:235], off
	s_and_saveexec_b64 s[56:57], s[2:3]
	s_cbranch_execz .LBB0_1864
	s_add_i32 s36, s68, 0
	s_add_i32 m0, s36, 0x22400
	s_nop 0
	global_load_lds_dwordx4 v[4:5], off
